# phase-start de-serialisation: SGU parameter loads waited for behind the unit's loads; attention bias-table values fetched at the start of the phase (one wait for everything prefetched before their fir
# speedup vs baseline: 1.0081x; 1.0079x over previous
.LBB0_427:
	s_or_b64 exec, exec, s[0:1]
	v_add_u32_e32 v13, 0x200, v96
	v_min_i32_e32 v0, 0xe87, v13
	v_ashrrev_i32_e32 v1, 31, v0
	v_add_u32_e32 v11, 0x400, v96
	v_lshl_add_u64 v[2:3], v[0:1], 2, s[26:27]
	v_min_i32_e32 v0, 0xe87, v11
	v_ashrrev_i32_e32 v1, 31, v0
	v_add_u32_e32 v9, 0x600, v96
	v_lshl_add_u64 v[16:17], v[0:1], 2, s[26:27]
	v_min_i32_e32 v0, 0xe87, v9
	v_ashrrev_i32_e32 v1, 31, v0
	v_add_u32_e32 v7, 0x800, v96
	v_lshl_add_u64 v[18:19], v[0:1], 2, s[26:27]
	v_min_i32_e32 v0, 0xe87, v7
	v_ashrrev_i32_e32 v1, 31, v0
	v_add_u32_e32 v6, 0xa00, v96
	v_lshl_add_u64 v[20:21], v[0:1], 2, s[26:27]
	v_min_i32_e32 v0, 0xe87, v6
	v_ashrrev_i32_e32 v1, 31, v0
	v_add_u32_e32 v4, 0xc00, v96
	v_lshl_add_u64 v[22:23], v[0:1], 2, s[26:27]
	v_min_i32_e32 v0, 0xe87, v4
	v_ashrrev_i32_e32 v1, 31, v0
	v_lshl_add_u64 v[24:25], v[0:1], 2, s[26:27]
	v_add_u32_e32 v0, 0xe00, v96
	v_min_i32_e32 v14, 0xe87, v0
	v_ashrrev_i32_e32 v15, 31, v14
	s_waitcnt lgkmcnt(0)
	s_barrier
	v_lshl_add_u64 v[26:27], v[14:15], 2, s[26:27]
	s_waitcnt vmcnt(0)
	v_mov_b32_e32 v15, v206
	v_mov_b32_e32 v14, v207
	v_mov_b32_e32 v12, v208
	v_mov_b32_e32 v10, v209
	v_mov_b32_e32 v8, v210
	v_mov_b32_e32 v5, v211
	v_mov_b32_e32 v1, v212
	s_movk_i32 s0, 0xe88
	v_cmp_gt_i32_e32 vcc, s0, v96
	v_mov_b32_e32 v2, 0
	v_lshlrev_b32_e32 v3, 2, v96
	s_and_saveexec_b64 s[0:1], vcc
	s_cbranch_execz .LBB0_429
	v_lshl_add_u64 v[16:17], v[96:97], 2, s[26:27]
	v_mov_b32_e32 v2, v205
	s_mov_b32 s4, 0x84210843
	v_mul_hi_i32 v16, v96, s4
	v_add_u32_e32 v16, v16, v96
	v_lshrrev_b32_e32 v17, 31, v16
	v_ashrrev_i32_e32 v16, 4, v16
	s_movk_i32 s5, 0xff84
	v_add_u32_e32 v16, v16, v17
	v_lshl_add_u32 v17, v16, 8, 0
	v_mul_lo_u32 v16, v16, s5
	v_add3_u32 v16, v17, v16, v3
	s_waitcnt vmcnt(0)
	v_mul_f32_e32 v2, 0x3fb8aa3b, v2
	ds_write_b32 v16, v2 offset:64
	v_max_f32_e64 v2, |v2|, 0
